# speedup vs baseline: 1.0005x; 1.0005x over previous
; __device__ __forceinline__ float sigm(float x) { return __builtin_amdgcn_rcpf(1.f + __expf(-x)); }
;     __device__ __forceinline__ void operator()(const f32x4 (&acc)[2][2][4][2], const Unit& u, int wr, int wc, int fr, int fq) const {
;     ...
;         for (int ai = 0; ai < 2; ++ai)
; #pragma unroll
;             for (int m = 0; m < 4; ++m) rs[ai][m] = rl[u.ui * 256 + ai * HALF + wr * 64 + m * 16 + fr];
;     ...
;             const int g = u.pn - 9, col0 = g * BM + wc * 32 + 8 * fq;
;             f32x4 bv[2][2];
; #pragma unroll
;             for (int bj = 0; bj < 2; ++bj)
; #pragma unroll
;                 for (int n = 0; n < 2; ++n) bv[bj][n] = *(const f32x4*)(bgate + col0 + bj * HALF + 4 * n);
; #pragma unroll
;             for (int ai = 0; ai < 2; ++ai)
; #pragma unroll
;                 for (int m = 0; m < 4; ++m) { unsigned char* rp = S + ((size_t)(((g >> 2) * (MT / 256) + u.pm) * 8 + (g & 3) * 2) * 256 + ai * HALF + wr * 64 + m * 16 + fr) * 128 + wc * 32 + 8 * fq;
; #pragma unroll
;                     for (int bj = 0; bj < 2; ++bj) { u32x2 w;
; #pragma unroll
;                         for (int n = 0; n < 2; ++n) { const f32x4 v = acc[ai][bj][m][n] * rs[ai][m] + bv[bj][n]; unsigned q = 0;
; #pragma unroll
;                             for (int j = 0; j < 4; ++j) { const unsigned b = (unsigned)(sigm(v[j]) * 255.f + 0.5f); q |= (b > 255u ? 255u : b) << (8 * j); }
;                             if (n == 0) w.x = q; else w.y = q; }
;                         *(u32x2*)(rp + (size_t)bj * 32768) = w; } }
.LBB0_289:
	v_lshl_add_u32 v128, s34, 10, v187
	ds_read2_b32 v[176:177], v128 offset1:16
	ds_read2_b32 v[174:175], v128 offset0:32 offset1:48
	ds_read2_b32 v[172:173], v128 offset0:128 offset1:144
	ds_read2_b32 v[170:171], v128 offset0:160 offset1:176
	s_cmp_gt_i32 s52, 8
	s_mov_b64 s[28:29], -1
	s_cbranch_scc0 .LBB0_291
	s_add_i32 s11, s52, -9
	v_lshl_or_b32 v144, s11, 8, v161
	v_lshl_add_u64 v[132:133], v[144:145], 2, s[14:15]
	global_load_dwordx4 v[136:139], v[132:133], off offset:16
	global_load_dwordx4 v[140:143], v[132:133], off
	global_load_dwordx4 v[128:131], v[132:133], off offset:528
	s_nop 0
	global_load_dwordx4 v[132:135], v[132:133], off offset:512
	s_lshr_b32 s21, s11, 2
	s_mulk_i32 s21, 0x84
	s_lshl_b32 s11, s11, 1
	s_add_i32 s21, s21, s53
	s_and_b32 s11, s11, 6
	s_lshl_b32 s21, s21, 3
	s_or_b32 s28, s21, s11
	s_ashr_i32 s29, s28, 31
	s_lshl_b64 s[28:29], s[28:29], 15
	v_lshl_add_u64 v[178:179], v[164:165], 0, s[28:29]
	v_lshl_add_u64 v[178:179], v[178:179], 0, s[72:73]
	v_lshl_add_u64 v[178:179], v[178:179], 0, v[162:163]
	s_mov_b32 s11, 0x9000
	s_mov_b64 s[28:29], 0
	s_waitcnt vmcnt(0) lgkmcnt(0)
	v_mul_f32_e32 v170, 0xbfb8aa3b, v170
	v_mul_f32_e32 v171, 0xbfb8aa3b, v171
	v_mul_f32_e32 v172, 0xbfb8aa3b, v172
	v_mul_f32_e32 v173, 0xbfb8aa3b, v173
	v_mul_f32_e32 v174, 0xbfb8aa3b, v174
	v_mul_f32_e32 v175, 0xbfb8aa3b, v175
	v_mul_f32_e32 v176, 0xbfb8aa3b, v176
	v_mul_f32_e32 v177, 0xbfb8aa3b, v177
	v_mul_f32_e32 v128, 0xbfb8aa3b, v128
	v_mul_f32_e32 v129, 0xbfb8aa3b, v129
	v_mul_f32_e32 v130, 0xbfb8aa3b, v130
	v_mul_f32_e32 v131, 0xbfb8aa3b, v131
	v_mul_f32_e32 v132, 0xbfb8aa3b, v132
	v_mul_f32_e32 v133, 0xbfb8aa3b, v133
	v_mul_f32_e32 v134, 0xbfb8aa3b, v134
	v_mul_f32_e32 v135, 0xbfb8aa3b, v135
	v_mul_f32_e32 v136, 0xbfb8aa3b, v136
	v_mul_f32_e32 v137, 0xbfb8aa3b, v137
	v_mul_f32_e32 v138, 0xbfb8aa3b, v138
	v_mul_f32_e32 v139, 0xbfb8aa3b, v139
	v_mul_f32_e32 v140, 0xbfb8aa3b, v140
	v_mul_f32_e32 v141, 0xbfb8aa3b, v141
	v_mul_f32_e32 v142, 0xbfb8aa3b, v142
	v_mul_f32_e32 v143, 0xbfb8aa3b, v143
	v_fma_f32 v182, v119, v176, v139
	v_fma_f32 v144, v124, v176, v140
	v_fma_f32 v180, v125, v176, v141
	v_exp_f32_e32 v144, v144
	v_exp_f32_e32 v180, v180
	v_fma_f32 v181, v127, v176, v143
	v_add_f32_e32 v144, 1.0, v144
	v_add_f32_e32 v180, 1.0, v180
	v_rcp_f32_e32 v144, v144
	v_rcp_f32_e32 v180, v180
	v_exp_f32_e32 v181, v181
	v_fma_f32 v144, v144, s82, 0.5
	v_fma_f32 v180, v180, s82, 0.5
	v_cvt_u32_f32_e32 v144, v144
	v_cvt_u32_f32_e32 v180, v180
	v_add_f32_e32 v181, 1.0, v181
	v_rcp_f32_e32 v181, v181
	v_lshl_or_b32 v144, v180, 8, v144
	v_fma_f32 v180, v126, v176, v142
	v_exp_f32_e32 v180, v180
	v_fma_f32 v181, v181, s82, 0.5
	v_cvt_u32_f32_e32 v181, v181
	v_exp_f32_e32 v182, v182
	v_add_f32_e32 v180, 1.0, v180
	v_rcp_f32_e32 v180, v180
	v_min_u32_sdwa v181, v181, s50 dst_sel:BYTE_3 dst_unused:UNUSED_PAD src0_sel:DWORD src1_sel:DWORD
	v_add_f32_e32 v182, 1.0, v182
	v_rcp_f32_e32 v182, v182
	v_fma_f32 v180, v180, s82, 0.5
	v_cvt_u32_f32_e32 v180, v180
	v_fma_f32 v189, v103, v177, v139
	v_fma_f32 v182, v182, s82, 0.5
	v_cvt_u32_f32_e32 v182, v182
	v_min_u32_sdwa v180, v180, s50 dst_sel:WORD_1 dst_unused:UNUSED_PAD src0_sel:DWORD src1_sel:DWORD
	s_nop 0
	v_or3_b32 v180, v144, v180, v181
	v_fma_f32 v144, v116, v176, v136
	v_fma_f32 v181, v117, v176, v137
	v_exp_f32_e32 v144, v144
	v_exp_f32_e32 v181, v181
	v_min_u32_sdwa v182, v182, s50 dst_sel:BYTE_3 dst_unused:UNUSED_PAD src0_sel:DWORD src1_sel:DWORD
	v_exp_f32_e32 v189, v189
	v_add_f32_e32 v144, 1.0, v144
	v_add_f32_e32 v181, 1.0, v181
	v_rcp_f32_e32 v144, v144
	v_rcp_f32_e32 v181, v181
	v_add_f32_e32 v189, 1.0, v189
	v_rcp_f32_e32 v189, v189
	v_fma_f32 v144, v144, s82, 0.5
	v_fma_f32 v181, v181, s82, 0.5
	v_cvt_u32_f32_e32 v144, v144
	v_cvt_u32_f32_e32 v181, v181
	v_fma_f32 v189, v189, s82, 0.5
	v_cvt_u32_f32_e32 v189, v189
	v_lshl_or_b32 v144, v181, 8, v144
	v_fma_f32 v181, v118, v176, v138
	v_exp_f32_e32 v181, v181
	v_min_u32_sdwa v189, v189, s50 dst_sel:BYTE_3 dst_unused:UNUSED_PAD src0_sel:DWORD src1_sel:DWORD
	v_add_f32_e32 v181, 1.0, v181
	v_rcp_f32_e32 v181, v181
	s_nop 0
	v_fma_f32 v181, v181, s82, 0.5
	v_cvt_u32_f32_e32 v181, v181
	v_min_u32_sdwa v181, v181, s50 dst_sel:WORD_1 dst_unused:UNUSED_PAD src0_sel:DWORD src1_sel:DWORD
	s_nop 0
	v_or3_b32 v181, v144, v181, v182
	global_store_dwordx2 v[178:179], v[180:181], off
	v_fma_f32 v144, v120, v176, v132
	v_fma_f32 v180, v121, v176, v133
	v_exp_f32_e32 v144, v144
	v_exp_f32_e32 v180, v180
	v_fma_f32 v181, v123, v176, v135
	v_add_f32_e32 v144, 1.0, v144
	v_add_f32_e32 v180, 1.0, v180
	v_rcp_f32_e32 v144, v144
	v_rcp_f32_e32 v180, v180
	v_exp_f32_e32 v181, v181
	v_add_co_u32_e32 v182, vcc, s25, v178
	v_fma_f32 v144, v144, s82, 0.5
	v_fma_f32 v180, v180, s82, 0.5
	v_cvt_u32_f32_e32 v144, v144
	v_cvt_u32_f32_e32 v180, v180
	v_add_f32_e32 v181, 1.0, v181
	v_rcp_f32_e32 v181, v181
	v_lshl_or_b32 v144, v180, 8, v144
	v_fma_f32 v180, v122, v176, v134
	v_exp_f32_e32 v180, v180
	v_fma_f32 v181, v181, s82, 0.5
	v_cvt_u32_f32_e32 v181, v181
	v_addc_co_u32_e32 v183, vcc, 0, v179, vcc
	v_add_f32_e32 v180, 1.0, v180
	v_rcp_f32_e32 v180, v180
	v_min_u32_sdwa v181, v181, s50 dst_sel:BYTE_3 dst_unused:UNUSED_PAD src0_sel:DWORD src1_sel:DWORD
	v_fma_f32 v180, v180, s82, 0.5
	v_cvt_u32_f32_e32 v180, v180
	v_min_u32_sdwa v180, v180, s50 dst_sel:WORD_1 dst_unused:UNUSED_PAD src0_sel:DWORD src1_sel:DWORD
	s_nop 0
	v_or3_b32 v184, v144, v180, v181
	v_fma_f32 v144, v112, v176, v128
	v_fma_f32 v180, v113, v176, v129
	v_exp_f32_e32 v144, v144
	v_exp_f32_e32 v180, v180
	v_fma_f32 v181, v115, v176, v131
	v_add_f32_e32 v144, 1.0, v144
	v_add_f32_e32 v180, 1.0, v180
; __device__ __forceinline__ float sigm(float x) { return __builtin_amdgcn_rcpf(1.f + __expf(-x)); }
;     __device__ __forceinline__ void operator()(const f32x4 (&acc)[2][2][4][2], const Unit& u, int wr, int wc, int fr, int fq) const {
;     ...
;             for (int ai = 0; ai < 2; ++ai)
; #pragma unroll
;                 for (int m = 0; m < 4; ++m) { unsigned char* rp = S + ((size_t)(((g >> 2) * (MT / 256) + u.pm) * 8 + (g & 3) * 2) * 256 + ai * HALF + wr * 64 + m * 16 + fr) * 128 + wc * 32 + 8 * fq;
; #pragma unroll
;                     for (int bj = 0; bj < 2; ++bj) { u32x2 w;
; #pragma unroll
;                         for (int n = 0; n < 2; ++n) { const f32x4 v = acc[ai][bj][m][n] * rs[ai][m] + bv[bj][n]; unsigned q = 0;
; #pragma unroll
;                             for (int j = 0; j < 4; ++j) { const unsigned b = (unsigned)(sigm(v[j]) * 255.f + 0.5f); q |= (b > 255u ? 255u : b) << (8 * j); }
;                             if (n == 0) w.x = q; else w.y = q; }
;                         *(u32x2*)(rp + (size_t)bj * 32768) = w; } }
	v_rcp_f32_e32 v144, v144
	v_rcp_f32_e32 v180, v180
	v_exp_f32_e32 v181, v181
	v_fma_f32 v144, v144, s82, 0.5
	v_fma_f32 v180, v180, s82, 0.5
	v_cvt_u32_f32_e32 v144, v144
	v_cvt_u32_f32_e32 v180, v180
	v_add_f32_e32 v181, 1.0, v181
	v_rcp_f32_e32 v181, v181
	v_lshl_or_b32 v144, v180, 8, v144
	v_fma_f32 v180, v114, v176, v130
	v_exp_f32_e32 v180, v180
	v_fma_f32 v181, v181, s82, 0.5
	v_cvt_u32_f32_e32 v181, v181
	v_add_f32_e32 v180, 1.0, v180
	v_rcp_f32_e32 v180, v180
	v_min_u32_sdwa v181, v181, s50 dst_sel:BYTE_3 dst_unused:UNUSED_PAD src0_sel:DWORD src1_sel:DWORD
	v_fma_f32 v180, v180, s82, 0.5
	v_cvt_u32_f32_e32 v180, v180
	v_min_u32_sdwa v180, v180, s50 dst_sel:WORD_1 dst_unused:UNUSED_PAD src0_sel:DWORD src1_sel:DWORD
	s_nop 0
	v_or3_b32 v185, v144, v180, v181
	v_add_co_u32_e32 v180, vcc, s11, v178
	v_fma_f32 v144, v108, v177, v140
	s_nop 0
	v_addc_co_u32_e32 v181, vcc, 0, v179, vcc
	global_store_dwordx2 v[180:181], v[184:185], off offset:-4096
	v_fma_f32 v184, v109, v177, v141
	v_exp_f32_e32 v144, v144
	v_exp_f32_e32 v184, v184
	v_fma_f32 v185, v111, v177, v143
	v_add_f32_e32 v144, 1.0, v144
	v_add_f32_e32 v184, 1.0, v184
	v_rcp_f32_e32 v144, v144
	v_rcp_f32_e32 v184, v184
	v_exp_f32_e32 v185, v185
	s_movk_i32 s11, 0x1000
	v_fma_f32 v144, v144, s82, 0.5
	v_fma_f32 v184, v184, s82, 0.5
	v_cvt_u32_f32_e32 v144, v144
	v_cvt_u32_f32_e32 v184, v184
	v_add_f32_e32 v185, 1.0, v185
	v_rcp_f32_e32 v185, v185
	v_lshl_or_b32 v144, v184, 8, v144
	v_fma_f32 v184, v110, v177, v142
	v_exp_f32_e32 v184, v184
	v_fma_f32 v185, v185, s82, 0.5
	v_cvt_u32_f32_e32 v185, v185
	v_add_f32_e32 v184, 1.0, v184
	v_rcp_f32_e32 v184, v184
	v_min_u32_sdwa v185, v185, s50 dst_sel:BYTE_3 dst_unused:UNUSED_PAD src0_sel:DWORD src1_sel:DWORD
	v_fma_f32 v184, v184, s82, 0.5
	v_cvt_u32_f32_e32 v184, v184
	v_min_u32_sdwa v184, v184, s50 dst_sel:WORD_1 dst_unused:UNUSED_PAD src0_sel:DWORD src1_sel:DWORD
	s_nop 0
	v_or3_b32 v184, v144, v184, v185
	v_fma_f32 v144, v100, v177, v136
	v_fma_f32 v185, v101, v177, v137
	v_exp_f32_e32 v144, v144
	v_exp_f32_e32 v185, v185
	v_add_f32_e32 v144, 1.0, v144
	v_add_f32_e32 v185, 1.0, v185
	v_rcp_f32_e32 v144, v144
	v_rcp_f32_e32 v185, v185
	v_fma_f32 v144, v144, s82, 0.5
	v_fma_f32 v185, v185, s82, 0.5
	v_cvt_u32_f32_e32 v144, v144
	v_cvt_u32_f32_e32 v185, v185
	v_lshl_or_b32 v144, v185, 8, v144
	v_fma_f32 v185, v102, v177, v138
	v_exp_f32_e32 v185, v185
	s_nop 0
	v_add_f32_e32 v185, 1.0, v185
	v_rcp_f32_e32 v185, v185
	s_nop 0
	v_fma_f32 v185, v185, s82, 0.5
	v_cvt_u32_f32_e32 v185, v185
	v_min_u32_sdwa v185, v185, s50 dst_sel:WORD_1 dst_unused:UNUSED_PAD src0_sel:DWORD src1_sel:DWORD
	s_nop 0
	v_or3_b32 v185, v144, v185, v189
	global_store_dwordx2 v[178:179], v[184:185], off offset:2048
	v_fma_f32 v144, v104, v177, v132
	v_fma_f32 v184, v105, v177, v133
	v_exp_f32_e32 v144, v144
	v_exp_f32_e32 v184, v184
	v_fma_f32 v185, v107, v177, v135
	v_add_f32_e32 v144, 1.0, v144
	v_add_f32_e32 v184, 1.0, v184
	v_rcp_f32_e32 v144, v144
	v_rcp_f32_e32 v184, v184
	v_exp_f32_e32 v185, v185
	v_fma_f32 v189, v99, v177, v131
	v_fma_f32 v144, v144, s82, 0.5
	v_fma_f32 v184, v184, s82, 0.5
	v_cvt_u32_f32_e32 v144, v144
	v_cvt_u32_f32_e32 v184, v184
	v_add_f32_e32 v185, 1.0, v185
	v_rcp_f32_e32 v185, v185
	v_lshl_or_b32 v144, v184, 8, v144
	v_fma_f32 v184, v106, v177, v134
	v_exp_f32_e32 v184, v184
	v_fma_f32 v185, v185, s82, 0.5
	v_cvt_u32_f32_e32 v185, v185
	v_add_f32_e32 v184, 1.0, v184
	v_rcp_f32_e32 v184, v184
	v_min_u32_sdwa v185, v185, s50 dst_sel:BYTE_3 dst_unused:UNUSED_PAD src0_sel:DWORD src1_sel:DWORD
	v_exp_f32_e32 v189, v189
	v_fma_f32 v184, v184, s82, 0.5
	v_cvt_u32_f32_e32 v184, v184
	v_add_f32_e32 v189, 1.0, v189
	v_rcp_f32_e32 v189, v189
	v_min_u32_sdwa v184, v184, s50 dst_sel:WORD_1 dst_unused:UNUSED_PAD src0_sel:DWORD src1_sel:DWORD
	s_nop 0
	v_or3_b32 v184, v144, v184, v185
	v_fma_f32 v144, v96, v177, v128
	v_fma_f32 v185, v97, v177, v129
	v_exp_f32_e32 v144, v144
	v_exp_f32_e32 v185, v185
	v_fma_f32 v189, v189, s82, 0.5
	v_cvt_u32_f32_e32 v189, v189
	v_add_f32_e32 v144, 1.0, v144
	v_add_f32_e32 v185, 1.0, v185
	v_rcp_f32_e32 v144, v144
	v_rcp_f32_e32 v185, v185
	v_min_u32_sdwa v189, v189, s50 dst_sel:BYTE_3 dst_unused:UNUSED_PAD src0_sel:DWORD src1_sel:DWORD
	v_fma_f32 v144, v144, s82, 0.5
	v_fma_f32 v185, v185, s82, 0.5
	v_cvt_u32_f32_e32 v144, v144
	v_cvt_u32_f32_e32 v185, v185
	v_lshl_or_b32 v144, v185, 8, v144
	v_fma_f32 v185, v98, v177, v130
	v_exp_f32_e32 v185, v185
	s_nop 0
	v_add_f32_e32 v185, 1.0, v185
	v_rcp_f32_e32 v185, v185
	s_nop 0
	v_fma_f32 v185, v185, s82, 0.5
	v_cvt_u32_f32_e32 v185, v185
	v_min_u32_sdwa v185, v185, s50 dst_sel:WORD_1 dst_unused:UNUSED_PAD src0_sel:DWORD src1_sel:DWORD
	s_nop 0
	v_or3_b32 v185, v144, v185, v189
	global_store_dwordx2 v[182:183], v[184:185], off offset:2048
	v_fma_f32 v144, v92, v174, v140
	v_fma_f32 v182, v93, v174, v141
	v_exp_f32_e32 v144, v144
	v_exp_f32_e32 v182, v182
	v_fma_f32 v183, v95, v174, v143
	v_add_f32_e32 v144, 1.0, v144
	v_add_f32_e32 v182, 1.0, v182
	v_rcp_f32_e32 v144, v144
	v_rcp_f32_e32 v182, v182
	v_exp_f32_e32 v183, v183
	v_fma_f32 v189, v83, v174, v131
	v_fma_f32 v144, v144, s82, 0.5
	v_fma_f32 v182, v182, s82, 0.5
	v_cvt_u32_f32_e32 v144, v144
	v_cvt_u32_f32_e32 v182, v182
	v_add_f32_e32 v183, 1.0, v183
	v_rcp_f32_e32 v183, v183
	v_lshl_or_b32 v144, v182, 8, v144
	v_fma_f32 v182, v94, v174, v142
	v_exp_f32_e32 v182, v182
	v_fma_f32 v183, v183, s82, 0.5
	v_cvt_u32_f32_e32 v183, v183
	v_add_f32_e32 v182, 1.0, v182
	v_rcp_f32_e32 v182, v182
	v_min_u32_sdwa v183, v183, s50 dst_sel:BYTE_3 dst_unused:UNUSED_PAD src0_sel:DWORD src1_sel:DWORD
	v_exp_f32_e32 v189, v189
; __device__ __forceinline__ float sigm(float x) { return __builtin_amdgcn_rcpf(1.f + __expf(-x)); }
;     __device__ __forceinline__ void operator()(const f32x4 (&acc)[2][2][4][2], const Unit& u, int wr, int wc, int fr, int fq) const {
;     ...
;             for (int ai = 0; ai < 2; ++ai)
; #pragma unroll
;                 for (int m = 0; m < 4; ++m) { unsigned char* rp = S + ((size_t)(((g >> 2) * (MT / 256) + u.pm) * 8 + (g & 3) * 2) * 256 + ai * HALF + wr * 64 + m * 16 + fr) * 128 + wc * 32 + 8 * fq;
; #pragma unroll
;                     for (int bj = 0; bj < 2; ++bj) { u32x2 w;
; #pragma unroll
;                         for (int n = 0; n < 2; ++n) { const f32x4 v = acc[ai][bj][m][n] * rs[ai][m] + bv[bj][n]; unsigned q = 0;
; #pragma unroll
;                             for (int j = 0; j < 4; ++j) { const unsigned b = (unsigned)(sigm(v[j]) * 255.f + 0.5f); q |= (b > 255u ? 255u : b) << (8 * j); }
;                             if (n == 0) w.x = q; else w.y = q; }
;                         *(u32x2*)(rp + (size_t)bj * 32768) = w; } }
	v_fma_f32 v182, v182, s82, 0.5
	v_cvt_u32_f32_e32 v182, v182
	v_add_f32_e32 v189, 1.0, v189
	v_rcp_f32_e32 v189, v189
	v_min_u32_sdwa v182, v182, s50 dst_sel:WORD_1 dst_unused:UNUSED_PAD src0_sel:DWORD src1_sel:DWORD
	s_nop 0
	v_or3_b32 v184, v144, v182, v183
	v_fma_f32 v144, v84, v174, v136
	v_fma_f32 v182, v85, v174, v137
	v_exp_f32_e32 v144, v144
	v_exp_f32_e32 v182, v182
	v_fma_f32 v183, v87, v174, v139
	v_add_f32_e32 v144, 1.0, v144
	v_add_f32_e32 v182, 1.0, v182
	v_rcp_f32_e32 v144, v144
	v_rcp_f32_e32 v182, v182
	v_exp_f32_e32 v183, v183
	v_fma_f32 v189, v189, s82, 0.5
	v_fma_f32 v144, v144, s82, 0.5
	v_fma_f32 v182, v182, s82, 0.5
	v_cvt_u32_f32_e32 v144, v144
	v_cvt_u32_f32_e32 v182, v182
	v_add_f32_e32 v183, 1.0, v183
	v_rcp_f32_e32 v183, v183
	v_lshl_or_b32 v144, v182, 8, v144
	v_fma_f32 v182, v86, v174, v138
	v_exp_f32_e32 v182, v182
	v_fma_f32 v183, v183, s82, 0.5
	v_cvt_u32_f32_e32 v183, v183
	v_cvt_u32_f32_e32 v189, v189
	v_add_f32_e32 v182, 1.0, v182
	v_rcp_f32_e32 v182, v182
	v_min_u32_sdwa v183, v183, s50 dst_sel:BYTE_3 dst_unused:UNUSED_PAD src0_sel:DWORD src1_sel:DWORD
	v_min_u32_sdwa v189, v189, s50 dst_sel:BYTE_3 dst_unused:UNUSED_PAD src0_sel:DWORD src1_sel:DWORD
	v_fma_f32 v182, v182, s82, 0.5
	v_cvt_u32_f32_e32 v182, v182
	v_min_u32_sdwa v182, v182, s50 dst_sel:WORD_1 dst_unused:UNUSED_PAD src0_sel:DWORD src1_sel:DWORD
	s_nop 0
	v_or3_b32 v185, v144, v182, v183
	v_add_co_u32_e32 v182, vcc, s11, v178
	v_fma_f32 v144, v88, v174, v132
	s_nop 0
	v_addc_co_u32_e32 v183, vcc, 0, v179, vcc
	global_store_dwordx2 v[182:183], v[184:185], off
	v_fma_f32 v184, v89, v174, v133
	v_exp_f32_e32 v144, v144
	v_exp_f32_e32 v184, v184
	v_fma_f32 v185, v91, v174, v135
	v_add_f32_e32 v144, 1.0, v144
	v_add_f32_e32 v184, 1.0, v184
	v_rcp_f32_e32 v144, v144
	v_rcp_f32_e32 v184, v184
	v_exp_f32_e32 v185, v185
	s_movk_i32 s11, 0x4000
	v_fma_f32 v144, v144, s82, 0.5
	v_fma_f32 v184, v184, s82, 0.5
	v_cvt_u32_f32_e32 v144, v144
	v_cvt_u32_f32_e32 v184, v184
	v_add_f32_e32 v185, 1.0, v185
	v_rcp_f32_e32 v185, v185
	v_lshl_or_b32 v144, v184, 8, v144
	v_fma_f32 v184, v90, v174, v134
	v_exp_f32_e32 v184, v184
	v_fma_f32 v185, v185, s82, 0.5
	v_cvt_u32_f32_e32 v185, v185
	v_add_f32_e32 v184, 1.0, v184
	v_rcp_f32_e32 v184, v184
	v_min_u32_sdwa v185, v185, s50 dst_sel:BYTE_3 dst_unused:UNUSED_PAD src0_sel:DWORD src1_sel:DWORD
	v_fma_f32 v184, v184, s82, 0.5
	v_cvt_u32_f32_e32 v184, v184
	v_min_u32_sdwa v184, v184, s50 dst_sel:WORD_1 dst_unused:UNUSED_PAD src0_sel:DWORD src1_sel:DWORD
	s_nop 0
	v_or3_b32 v184, v144, v184, v185
	v_fma_f32 v144, v80, v174, v128
	v_fma_f32 v185, v81, v174, v129
	v_exp_f32_e32 v144, v144
	v_exp_f32_e32 v185, v185
	v_add_f32_e32 v144, 1.0, v144
	v_add_f32_e32 v185, 1.0, v185
	v_rcp_f32_e32 v144, v144
	v_rcp_f32_e32 v185, v185
	v_fma_f32 v144, v144, s82, 0.5
	v_fma_f32 v185, v185, s82, 0.5
	v_cvt_u32_f32_e32 v144, v144
	v_cvt_u32_f32_e32 v185, v185
	v_lshl_or_b32 v144, v185, 8, v144
	v_fma_f32 v185, v82, v174, v130
	v_exp_f32_e32 v185, v185
	s_nop 0
	v_add_f32_e32 v185, 1.0, v185
	v_rcp_f32_e32 v185, v185
	s_nop 0
	v_fma_f32 v185, v185, s82, 0.5
	v_cvt_u32_f32_e32 v185, v185
	v_min_u32_sdwa v185, v185, s50 dst_sel:WORD_1 dst_unused:UNUSED_PAD src0_sel:DWORD src1_sel:DWORD
	s_nop 0
	v_or3_b32 v185, v144, v185, v189
	global_store_dwordx2 v[180:181], v[184:185], off
	v_fma_f32 v144, v76, v175, v140
	v_fma_f32 v184, v77, v175, v141
	v_exp_f32_e32 v144, v144
	v_exp_f32_e32 v184, v184
	v_fma_f32 v185, v79, v175, v143
	v_add_f32_e32 v144, 1.0, v144
	v_add_f32_e32 v184, 1.0, v184
	v_rcp_f32_e32 v144, v144
	v_rcp_f32_e32 v184, v184
	v_exp_f32_e32 v185, v185
	v_fma_f32 v189, v71, v175, v139
	v_fma_f32 v144, v144, s82, 0.5
	v_fma_f32 v184, v184, s82, 0.5
	v_cvt_u32_f32_e32 v144, v144
	v_cvt_u32_f32_e32 v184, v184
	v_add_f32_e32 v185, 1.0, v185
	v_rcp_f32_e32 v185, v185
	v_lshl_or_b32 v144, v184, 8, v144
	v_fma_f32 v184, v78, v175, v142
	v_exp_f32_e32 v184, v184
	v_fma_f32 v185, v185, s82, 0.5
	v_cvt_u32_f32_e32 v185, v185
	v_add_f32_e32 v184, 1.0, v184
	v_rcp_f32_e32 v184, v184
	v_min_u32_sdwa v185, v185, s50 dst_sel:BYTE_3 dst_unused:UNUSED_PAD src0_sel:DWORD src1_sel:DWORD
	v_exp_f32_e32 v189, v189
	v_fma_f32 v184, v184, s82, 0.5
	v_cvt_u32_f32_e32 v184, v184
	v_add_f32_e32 v189, 1.0, v189
	v_rcp_f32_e32 v189, v189
	v_min_u32_sdwa v184, v184, s50 dst_sel:WORD_1 dst_unused:UNUSED_PAD src0_sel:DWORD src1_sel:DWORD
	s_nop 0
	v_or3_b32 v184, v144, v184, v185
	v_fma_f32 v144, v68, v175, v136
	v_fma_f32 v185, v69, v175, v137
	v_exp_f32_e32 v144, v144
	v_exp_f32_e32 v185, v185
	v_fma_f32 v189, v189, s82, 0.5
	v_cvt_u32_f32_e32 v189, v189
	v_add_f32_e32 v144, 1.0, v144
	v_add_f32_e32 v185, 1.0, v185
	v_rcp_f32_e32 v144, v144
	v_rcp_f32_e32 v185, v185
	v_min_u32_sdwa v189, v189, s50 dst_sel:BYTE_3 dst_unused:UNUSED_PAD src0_sel:DWORD src1_sel:DWORD
	v_fma_f32 v144, v144, s82, 0.5
	v_fma_f32 v185, v185, s82, 0.5
	v_cvt_u32_f32_e32 v144, v144
	v_cvt_u32_f32_e32 v185, v185
	v_lshl_or_b32 v144, v185, 8, v144
	v_fma_f32 v185, v70, v175, v138
	v_exp_f32_e32 v185, v185
	s_nop 0
	v_add_f32_e32 v185, 1.0, v185
	v_rcp_f32_e32 v185, v185
	s_nop 0
	v_fma_f32 v185, v185, s82, 0.5
	v_cvt_u32_f32_e32 v185, v185
	v_min_u32_sdwa v185, v185, s50 dst_sel:WORD_1 dst_unused:UNUSED_PAD src0_sel:DWORD src1_sel:DWORD
	s_nop 0
	v_or3_b32 v185, v144, v185, v189
	global_store_dwordx2 v[182:183], v[184:185], off offset:2048
	v_fma_f32 v144, v72, v175, v132
	v_fma_f32 v182, v73, v175, v133
	v_exp_f32_e32 v144, v144
	v_exp_f32_e32 v182, v182
	v_fma_f32 v183, v75, v175, v135
	v_add_f32_e32 v144, 1.0, v144
	v_add_f32_e32 v182, 1.0, v182
	v_rcp_f32_e32 v144, v144
; __device__ __forceinline__ float sigm(float x) { return __builtin_amdgcn_rcpf(1.f + __expf(-x)); }
;     __device__ __forceinline__ void operator()(const f32x4 (&acc)[2][2][4][2], const Unit& u, int wr, int wc, int fr, int fq) const {
;     ...
;             for (int ai = 0; ai < 2; ++ai)
; #pragma unroll
;                 for (int m = 0; m < 4; ++m) { unsigned char* rp = S + ((size_t)(((g >> 2) * (MT / 256) + u.pm) * 8 + (g & 3) * 2) * 256 + ai * HALF + wr * 64 + m * 16 + fr) * 128 + wc * 32 + 8 * fq;
; #pragma unroll
;                     for (int bj = 0; bj < 2; ++bj) { u32x2 w;
; #pragma unroll
;                         for (int n = 0; n < 2; ++n) { const f32x4 v = acc[ai][bj][m][n] * rs[ai][m] + bv[bj][n]; unsigned q = 0;
; #pragma unroll
;                             for (int j = 0; j < 4; ++j) { const unsigned b = (unsigned)(sigm(v[j]) * 255.f + 0.5f); q |= (b > 255u ? 255u : b) << (8 * j); }
;                             if (n == 0) w.x = q; else w.y = q; }
;                         *(u32x2*)(rp + (size_t)bj * 32768) = w; } }
	v_rcp_f32_e32 v182, v182
	v_exp_f32_e32 v183, v183
	v_fma_f32 v184, v67, v175, v131
	v_fma_f32 v144, v144, s82, 0.5
	v_fma_f32 v182, v182, s82, 0.5
	v_cvt_u32_f32_e32 v144, v144
	v_cvt_u32_f32_e32 v182, v182
	v_add_f32_e32 v183, 1.0, v183
	v_rcp_f32_e32 v183, v183
	v_lshl_or_b32 v144, v182, 8, v144
	v_fma_f32 v182, v74, v175, v134
	v_exp_f32_e32 v182, v182
	v_fma_f32 v183, v183, s82, 0.5
	v_cvt_u32_f32_e32 v183, v183
	v_add_f32_e32 v182, 1.0, v182
	v_rcp_f32_e32 v182, v182
	v_min_u32_sdwa v183, v183, s50 dst_sel:BYTE_3 dst_unused:UNUSED_PAD src0_sel:DWORD src1_sel:DWORD
	v_exp_f32_e32 v184, v184
	v_fma_f32 v189, v45, v173, v141
	v_fma_f32 v182, v182, s82, 0.5
	v_cvt_u32_f32_e32 v182, v182
	v_add_f32_e32 v184, 1.0, v184
	v_rcp_f32_e32 v184, v184
	v_min_u32_sdwa v182, v182, s50 dst_sel:WORD_1 dst_unused:UNUSED_PAD src0_sel:DWORD src1_sel:DWORD
	v_exp_f32_e32 v189, v189
	v_or3_b32 v182, v144, v182, v183
	v_fma_f32 v144, v64, v175, v128
	v_fma_f32 v183, v65, v175, v129
	v_exp_f32_e32 v144, v144
	v_exp_f32_e32 v183, v183
	v_fma_f32 v184, v184, s82, 0.5
	v_cvt_u32_f32_e32 v184, v184
	v_add_f32_e32 v144, 1.0, v144
	v_add_f32_e32 v183, 1.0, v183
	v_rcp_f32_e32 v144, v144
	v_rcp_f32_e32 v183, v183
	v_min_u32_sdwa v184, v184, s50 dst_sel:BYTE_3 dst_unused:UNUSED_PAD src0_sel:DWORD src1_sel:DWORD
	v_add_f32_e32 v189, 1.0, v189
	v_fma_f32 v144, v144, s82, 0.5
	v_fma_f32 v183, v183, s82, 0.5
	v_cvt_u32_f32_e32 v144, v144
	v_cvt_u32_f32_e32 v183, v183
	v_rcp_f32_e32 v189, v189
	v_lshl_or_b32 v144, v183, 8, v144
	v_fma_f32 v183, v66, v175, v130
	v_exp_f32_e32 v183, v183
	v_fma_f32 v189, v189, s82, 0.5
	v_cvt_u32_f32_e32 v189, v189
	v_add_f32_e32 v183, 1.0, v183
	v_rcp_f32_e32 v183, v183
	s_nop 0
	v_fma_f32 v183, v183, s82, 0.5
	v_cvt_u32_f32_e32 v183, v183
	v_min_u32_sdwa v183, v183, s50 dst_sel:WORD_1 dst_unused:UNUSED_PAD src0_sel:DWORD src1_sel:DWORD
	s_nop 0
	v_or3_b32 v183, v144, v183, v184
	global_store_dwordx2 v[180:181], v[182:183], off offset:2048
	v_fma_f32 v144, v60, v172, v140
	v_fma_f32 v180, v61, v172, v141
	v_exp_f32_e32 v144, v144
	v_exp_f32_e32 v180, v180
	v_fma_f32 v181, v63, v172, v143
	v_add_f32_e32 v144, 1.0, v144
	v_add_f32_e32 v180, 1.0, v180
	v_rcp_f32_e32 v144, v144
	v_rcp_f32_e32 v180, v180
	v_exp_f32_e32 v181, v181
	v_add_co_u32_e32 v182, vcc, s11, v178
	v_fma_f32 v144, v144, s82, 0.5
	v_fma_f32 v180, v180, s82, 0.5
	v_cvt_u32_f32_e32 v144, v144
	v_cvt_u32_f32_e32 v180, v180
	v_add_f32_e32 v181, 1.0, v181
	v_rcp_f32_e32 v181, v181
	v_lshl_or_b32 v144, v180, 8, v144
	v_fma_f32 v180, v62, v172, v142
	v_exp_f32_e32 v180, v180
	v_fma_f32 v181, v181, s82, 0.5
	v_cvt_u32_f32_e32 v181, v181
	v_addc_co_u32_e32 v183, vcc, 0, v179, vcc
	v_add_f32_e32 v180, 1.0, v180
	v_rcp_f32_e32 v180, v180
	v_min_u32_sdwa v181, v181, s50 dst_sel:BYTE_3 dst_unused:UNUSED_PAD src0_sel:DWORD src1_sel:DWORD
	s_movk_i32 s11, 0x5000
	v_fma_f32 v180, v180, s82, 0.5
	v_cvt_u32_f32_e32 v180, v180
	v_min_u32_sdwa v180, v180, s50 dst_sel:WORD_1 dst_unused:UNUSED_PAD src0_sel:DWORD src1_sel:DWORD
	s_nop 0
	v_or3_b32 v184, v144, v180, v181
	v_fma_f32 v144, v52, v172, v136
	v_fma_f32 v180, v53, v172, v137
	v_exp_f32_e32 v144, v144
	v_exp_f32_e32 v180, v180
	v_fma_f32 v181, v55, v172, v139
	v_add_f32_e32 v144, 1.0, v144
	v_add_f32_e32 v180, 1.0, v180
	v_rcp_f32_e32 v144, v144
	v_rcp_f32_e32 v180, v180
	v_exp_f32_e32 v181, v181
	v_fma_f32 v144, v144, s82, 0.5
	v_fma_f32 v180, v180, s82, 0.5
	v_cvt_u32_f32_e32 v144, v144
	v_cvt_u32_f32_e32 v180, v180
	v_add_f32_e32 v181, 1.0, v181
	v_rcp_f32_e32 v181, v181
	v_lshl_or_b32 v144, v180, 8, v144
	v_fma_f32 v180, v54, v172, v138
	v_exp_f32_e32 v180, v180
	v_fma_f32 v181, v181, s82, 0.5
	v_cvt_u32_f32_e32 v181, v181
	v_add_f32_e32 v180, 1.0, v180
	v_rcp_f32_e32 v180, v180
	v_min_u32_sdwa v181, v181, s50 dst_sel:BYTE_3 dst_unused:UNUSED_PAD src0_sel:DWORD src1_sel:DWORD
	v_fma_f32 v180, v180, s82, 0.5
	v_cvt_u32_f32_e32 v180, v180
	v_min_u32_sdwa v180, v180, s50 dst_sel:WORD_1 dst_unused:UNUSED_PAD src0_sel:DWORD src1_sel:DWORD
	s_nop 0
	v_or3_b32 v185, v144, v180, v181
	v_add_co_u32_e32 v180, vcc, s11, v178
	v_fma_f32 v144, v56, v172, v132
	s_nop 0
	v_addc_co_u32_e32 v181, vcc, 0, v179, vcc
	global_store_dwordx2 v[180:181], v[184:185], off offset:-4096
	v_fma_f32 v184, v57, v172, v133
	v_exp_f32_e32 v144, v144
	v_exp_f32_e32 v184, v184
	v_fma_f32 v185, v59, v172, v135
	v_add_f32_e32 v144, 1.0, v144
	v_add_f32_e32 v184, 1.0, v184
	v_rcp_f32_e32 v144, v144
	v_rcp_f32_e32 v184, v184
	v_exp_f32_e32 v185, v185
	s_mov_b32 s11, 0xc000
	v_fma_f32 v144, v144, s82, 0.5
	v_fma_f32 v184, v184, s82, 0.5
	v_cvt_u32_f32_e32 v144, v144
	v_cvt_u32_f32_e32 v184, v184
	v_add_f32_e32 v185, 1.0, v185
	v_rcp_f32_e32 v185, v185
	v_lshl_or_b32 v144, v184, 8, v144
	v_fma_f32 v184, v58, v172, v134
	v_exp_f32_e32 v184, v184
	v_fma_f32 v185, v185, s82, 0.5
	v_cvt_u32_f32_e32 v185, v185
	v_add_f32_e32 v184, 1.0, v184
	v_rcp_f32_e32 v184, v184
	v_min_u32_sdwa v185, v185, s50 dst_sel:BYTE_3 dst_unused:UNUSED_PAD src0_sel:DWORD src1_sel:DWORD
	v_fma_f32 v184, v184, s82, 0.5
	v_cvt_u32_f32_e32 v184, v184
	v_min_u32_sdwa v184, v184, s50 dst_sel:WORD_1 dst_unused:UNUSED_PAD src0_sel:DWORD src1_sel:DWORD
	s_nop 0
	v_or3_b32 v190, v144, v184, v185
	v_fma_f32 v144, v48, v172, v128
	v_fma_f32 v184, v49, v172, v129
	v_exp_f32_e32 v144, v144
	v_exp_f32_e32 v184, v184
	v_fma_f32 v185, v51, v172, v131
	v_add_f32_e32 v144, 1.0, v144
	v_add_f32_e32 v184, 1.0, v184
	v_rcp_f32_e32 v144, v144
	v_rcp_f32_e32 v184, v184
	v_exp_f32_e32 v185, v185
	v_fma_f32 v144, v144, s82, 0.5
	v_fma_f32 v184, v184, s82, 0.5
	v_cvt_u32_f32_e32 v144, v144
	v_cvt_u32_f32_e32 v184, v184
; __device__ __forceinline__ float sigm(float x) { return __builtin_amdgcn_rcpf(1.f + __expf(-x)); }
;     __device__ __forceinline__ void operator()(const f32x4 (&acc)[2][2][4][2], const Unit& u, int wr, int wc, int fr, int fq) const {
;     ...
;             for (int ai = 0; ai < 2; ++ai)
; #pragma unroll
;                 for (int m = 0; m < 4; ++m) { unsigned char* rp = S + ((size_t)(((g >> 2) * (MT / 256) + u.pm) * 8 + (g & 3) * 2) * 256 + ai * HALF + wr * 64 + m * 16 + fr) * 128 + wc * 32 + 8 * fq;
; #pragma unroll
;                     for (int bj = 0; bj < 2; ++bj) { u32x2 w;
; #pragma unroll
;                         for (int n = 0; n < 2; ++n) { const f32x4 v = acc[ai][bj][m][n] * rs[ai][m] + bv[bj][n]; unsigned q = 0;
; #pragma unroll
;                             for (int j = 0; j < 4; ++j) { const unsigned b = (unsigned)(sigm(v[j]) * 255.f + 0.5f); q |= (b > 255u ? 255u : b) << (8 * j); }
;                             if (n == 0) w.x = q; else w.y = q; }
;                         *(u32x2*)(rp + (size_t)bj * 32768) = w; } }
	v_add_f32_e32 v185, 1.0, v185
	v_rcp_f32_e32 v185, v185
	v_lshl_or_b32 v144, v184, 8, v144
	v_fma_f32 v184, v50, v172, v130
	v_exp_f32_e32 v184, v184
	v_fma_f32 v185, v185, s82, 0.5
	v_cvt_u32_f32_e32 v185, v185
	v_add_f32_e32 v184, 1.0, v184
	v_rcp_f32_e32 v184, v184
	v_min_u32_sdwa v185, v185, s50 dst_sel:BYTE_3 dst_unused:UNUSED_PAD src0_sel:DWORD src1_sel:DWORD
	v_fma_f32 v184, v184, s82, 0.5
	v_cvt_u32_f32_e32 v184, v184
	v_min_u32_sdwa v184, v184, s50 dst_sel:WORD_1 dst_unused:UNUSED_PAD src0_sel:DWORD src1_sel:DWORD
	s_nop 0
	v_or3_b32 v191, v144, v184, v185
	v_fma_f32 v144, v44, v173, v140
	v_exp_f32_e32 v144, v144
	v_add_co_u32_e32 v184, vcc, s11, v178
	s_mov_b32 s11, 0xd000
	v_add_f32_e32 v144, 1.0, v144
	v_rcp_f32_e32 v144, v144
	v_addc_co_u32_e32 v185, vcc, 0, v179, vcc
	v_add_co_u32_e32 v178, vcc, s11, v178
	v_fma_f32 v144, v144, s82, 0.5
	v_cvt_u32_f32_e32 v144, v144
	v_addc_co_u32_e32 v179, vcc, 0, v179, vcc
	global_store_dwordx2 v[178:179], v[190:191], off offset:-4096
	v_lshl_or_b32 v144, v189, 8, v144
	v_fma_f32 v189, v46, v173, v142
	v_fma_f32 v190, v47, v173, v143
	v_exp_f32_e32 v189, v189
	v_exp_f32_e32 v190, v190
	v_fma_f32 v191, v39, v173, v139
	v_add_f32_e32 v189, 1.0, v189
	v_add_f32_e32 v190, 1.0, v190
	v_rcp_f32_e32 v189, v189
	v_rcp_f32_e32 v190, v190
	v_exp_f32_e32 v191, v191
	v_fma_f32 v189, v189, s82, 0.5
	v_fma_f32 v190, v190, s82, 0.5
	v_cvt_u32_f32_e32 v189, v189
	v_cvt_u32_f32_e32 v190, v190
	v_add_f32_e32 v191, 1.0, v191
	v_rcp_f32_e32 v191, v191
	v_min_u32_sdwa v189, v189, s50 dst_sel:WORD_1 dst_unused:UNUSED_PAD src0_sel:DWORD src1_sel:DWORD
	v_min_u32_sdwa v190, v190, s50 dst_sel:BYTE_3 dst_unused:UNUSED_PAD src0_sel:DWORD src1_sel:DWORD
	v_fma_f32 v191, v191, s82, 0.5
	v_or3_b32 v190, v144, v189, v190
	v_fma_f32 v144, v36, v173, v136
	v_fma_f32 v189, v37, v173, v137
	v_exp_f32_e32 v144, v144
	v_exp_f32_e32 v189, v189
	v_cvt_u32_f32_e32 v191, v191
	v_add_f32_e32 v144, 1.0, v144
	v_add_f32_e32 v189, 1.0, v189
	v_rcp_f32_e32 v144, v144
	v_rcp_f32_e32 v189, v189
	v_min_u32_sdwa v191, v191, s50 dst_sel:BYTE_3 dst_unused:UNUSED_PAD src0_sel:DWORD src1_sel:DWORD
	v_fma_f32 v144, v144, s82, 0.5
	v_fma_f32 v189, v189, s82, 0.5
	v_cvt_u32_f32_e32 v144, v144
	v_cvt_u32_f32_e32 v189, v189
	v_lshl_or_b32 v144, v189, 8, v144
	v_fma_f32 v189, v38, v173, v138
	v_exp_f32_e32 v189, v189
	s_nop 0
	v_add_f32_e32 v189, 1.0, v189
	v_rcp_f32_e32 v189, v189
	s_nop 0
	v_fma_f32 v189, v189, s82, 0.5
	v_cvt_u32_f32_e32 v189, v189
	v_min_u32_sdwa v189, v189, s50 dst_sel:WORD_1 dst_unused:UNUSED_PAD src0_sel:DWORD src1_sel:DWORD
	s_nop 0
	v_or3_b32 v191, v144, v189, v191
	global_store_dwordx2 v[182:183], v[190:191], off offset:2048
	v_fma_f32 v144, v40, v173, v132
	v_fma_f32 v182, v41, v173, v133
	v_exp_f32_e32 v144, v144
	v_exp_f32_e32 v182, v182
	v_fma_f32 v183, v43, v173, v135
	v_add_f32_e32 v144, 1.0, v144
	v_add_f32_e32 v182, 1.0, v182
	v_rcp_f32_e32 v144, v144
	v_rcp_f32_e32 v182, v182
	v_exp_f32_e32 v183, v183
	v_fma_f32 v189, v35, v173, v131
	v_fma_f32 v144, v144, s82, 0.5
	v_fma_f32 v182, v182, s82, 0.5
	v_cvt_u32_f32_e32 v144, v144
	v_cvt_u32_f32_e32 v182, v182
	v_add_f32_e32 v183, 1.0, v183
	v_rcp_f32_e32 v183, v183
	v_lshl_or_b32 v144, v182, 8, v144
	v_fma_f32 v182, v42, v173, v134
	v_exp_f32_e32 v182, v182
	v_fma_f32 v183, v183, s82, 0.5
	v_cvt_u32_f32_e32 v183, v183
	v_add_f32_e32 v182, 1.0, v182
	v_rcp_f32_e32 v182, v182
	v_min_u32_sdwa v183, v183, s50 dst_sel:BYTE_3 dst_unused:UNUSED_PAD src0_sel:DWORD src1_sel:DWORD
	v_exp_f32_e32 v189, v189
	v_fma_f32 v182, v182, s82, 0.5
	v_cvt_u32_f32_e32 v182, v182
	v_add_f32_e32 v189, 1.0, v189
	v_rcp_f32_e32 v189, v189
	v_min_u32_sdwa v182, v182, s50 dst_sel:WORD_1 dst_unused:UNUSED_PAD src0_sel:DWORD src1_sel:DWORD
	s_nop 0
	v_or3_b32 v182, v144, v182, v183
	v_fma_f32 v144, v32, v173, v128
	v_fma_f32 v183, v33, v173, v129
	v_exp_f32_e32 v144, v144
	v_exp_f32_e32 v183, v183
	v_fma_f32 v189, v189, s82, 0.5
	v_cvt_u32_f32_e32 v189, v189
	v_add_f32_e32 v144, 1.0, v144
	v_add_f32_e32 v183, 1.0, v183
	v_rcp_f32_e32 v144, v144
	v_rcp_f32_e32 v183, v183
	v_min_u32_sdwa v189, v189, s50 dst_sel:BYTE_3 dst_unused:UNUSED_PAD src0_sel:DWORD src1_sel:DWORD
	v_fma_f32 v144, v144, s82, 0.5
	v_fma_f32 v183, v183, s82, 0.5
	v_cvt_u32_f32_e32 v144, v144
	v_cvt_u32_f32_e32 v183, v183
	v_lshl_or_b32 v144, v183, 8, v144
	v_fma_f32 v183, v34, v173, v130
	v_exp_f32_e32 v183, v183
	s_nop 0
	v_add_f32_e32 v183, 1.0, v183
	v_rcp_f32_e32 v183, v183
	s_nop 0
	v_fma_f32 v183, v183, s82, 0.5
	v_cvt_u32_f32_e32 v183, v183
	v_min_u32_sdwa v183, v183, s50 dst_sel:WORD_1 dst_unused:UNUSED_PAD src0_sel:DWORD src1_sel:DWORD
	s_nop 0
	v_or3_b32 v183, v144, v183, v189
	global_store_dwordx2 v[184:185], v[182:183], off offset:2048
	v_fma_f32 v144, v28, v170, v140
	v_fma_f32 v182, v29, v170, v141
	v_exp_f32_e32 v144, v144
	v_exp_f32_e32 v182, v182
	v_fma_f32 v183, v31, v170, v143
	v_add_f32_e32 v144, 1.0, v144
	v_add_f32_e32 v182, 1.0, v182
	v_rcp_f32_e32 v144, v144
	v_rcp_f32_e32 v182, v182
	v_exp_f32_e32 v183, v183
	v_fma_f32 v184, v23, v170, v139
	v_fma_f32 v144, v144, s82, 0.5
	v_fma_f32 v182, v182, s82, 0.5
	v_cvt_u32_f32_e32 v144, v144
	v_cvt_u32_f32_e32 v182, v182
	v_add_f32_e32 v183, 1.0, v183
	v_rcp_f32_e32 v183, v183
	v_lshl_or_b32 v144, v182, 8, v144
	v_fma_f32 v182, v30, v170, v142
	v_exp_f32_e32 v182, v182
	v_fma_f32 v183, v183, s82, 0.5
	v_cvt_u32_f32_e32 v183, v183
	v_add_f32_e32 v182, 1.0, v182
	v_rcp_f32_e32 v182, v182
	v_min_u32_sdwa v183, v183, s50 dst_sel:BYTE_3 dst_unused:UNUSED_PAD src0_sel:DWORD src1_sel:DWORD
	v_exp_f32_e32 v184, v184
	v_fma_f32 v140, v12, v171, v140
; __device__ __forceinline__ float sigm(float x) { return __builtin_amdgcn_rcpf(1.f + __expf(-x)); }
;     __device__ __forceinline__ void operator()(const f32x4 (&acc)[2][2][4][2], const Unit& u, int wr, int wc, int fr, int fq) const {
;     ...
;             for (int ai = 0; ai < 2; ++ai)
; #pragma unroll
;                 for (int m = 0; m < 4; ++m) { unsigned char* rp = S + ((size_t)(((g >> 2) * (MT / 256) + u.pm) * 8 + (g & 3) * 2) * 256 + ai * HALF + wr * 64 + m * 16 + fr) * 128 + wc * 32 + 8 * fq;
; #pragma unroll
;                     for (int bj = 0; bj < 2; ++bj) { u32x2 w;
; #pragma unroll
;                         for (int n = 0; n < 2; ++n) { const f32x4 v = acc[ai][bj][m][n] * rs[ai][m] + bv[bj][n]; unsigned q = 0;
; #pragma unroll
;                             for (int j = 0; j < 4; ++j) { const unsigned b = (unsigned)(sigm(v[j]) * 255.f + 0.5f); q |= (b > 255u ? 255u : b) << (8 * j); }
;                             if (n == 0) w.x = q; else w.y = q; }
;                         *(u32x2*)(rp + (size_t)bj * 32768) = w; } }
	v_fma_f32 v182, v182, s82, 0.5
	v_cvt_u32_f32_e32 v182, v182
	v_add_f32_e32 v184, 1.0, v184
	v_rcp_f32_e32 v184, v184
	v_fma_f32 v141, v13, v171, v141
	v_min_u32_sdwa v182, v182, s50 dst_sel:WORD_1 dst_unused:UNUSED_PAD src0_sel:DWORD src1_sel:DWORD
	s_nop 0
	v_or3_b32 v182, v144, v182, v183
	v_fma_f32 v144, v20, v170, v136
	v_fma_f32 v183, v21, v170, v137
	v_exp_f32_e32 v144, v144
	v_exp_f32_e32 v183, v183
	v_fma_f32 v184, v184, s82, 0.5
	v_cvt_u32_f32_e32 v184, v184
	v_add_f32_e32 v144, 1.0, v144
	v_add_f32_e32 v183, 1.0, v183
	v_rcp_f32_e32 v144, v144
	v_rcp_f32_e32 v183, v183
	v_min_u32_sdwa v184, v184, s50 dst_sel:BYTE_3 dst_unused:UNUSED_PAD src0_sel:DWORD src1_sel:DWORD
	v_fma_f32 v136, v4, v171, v136
	v_fma_f32 v144, v144, s82, 0.5
	v_fma_f32 v183, v183, s82, 0.5
	v_cvt_u32_f32_e32 v144, v144
	v_cvt_u32_f32_e32 v183, v183
	v_fma_f32 v137, v5, v171, v137
	v_lshl_or_b32 v144, v183, 8, v144
	v_fma_f32 v183, v22, v170, v138
	v_exp_f32_e32 v183, v183
	v_exp_f32_e32 v140, v140
	v_add_f32_e32 v183, 1.0, v183
	v_rcp_f32_e32 v183, v183
	v_exp_f32_e32 v141, v141
	v_exp_f32_e32 v136, v136
	v_exp_f32_e32 v137, v137
	v_fma_f32 v183, v183, s82, 0.5
	v_cvt_u32_f32_e32 v183, v183
	v_add_f32_e32 v140, 1.0, v140
	v_add_f32_e32 v141, 1.0, v141
	v_add_f32_e32 v136, 1.0, v136
	v_min_u32_sdwa v183, v183, s50 dst_sel:WORD_1 dst_unused:UNUSED_PAD src0_sel:DWORD src1_sel:DWORD
	v_add_f32_e32 v137, 1.0, v137
	v_or3_b32 v183, v144, v183, v184
	global_store_dwordx2 v[180:181], v[182:183], off
	v_fma_f32 v144, v24, v170, v132
	v_fma_f32 v182, v25, v170, v133
	v_exp_f32_e32 v144, v144
	v_exp_f32_e32 v182, v182
	v_fma_f32 v183, v27, v170, v135
	v_add_f32_e32 v144, 1.0, v144
	v_add_f32_e32 v182, 1.0, v182
	v_rcp_f32_e32 v144, v144
	v_rcp_f32_e32 v182, v182
	v_exp_f32_e32 v183, v183
	v_fma_f32 v132, v8, v171, v132
	v_fma_f32 v144, v144, s82, 0.5
	v_fma_f32 v182, v182, s82, 0.5
	v_cvt_u32_f32_e32 v144, v144
	v_cvt_u32_f32_e32 v182, v182
	v_add_f32_e32 v183, 1.0, v183
	v_rcp_f32_e32 v183, v183
	v_lshl_or_b32 v144, v182, 8, v144
	v_fma_f32 v182, v26, v170, v134
	v_exp_f32_e32 v182, v182
	v_fma_f32 v183, v183, s82, 0.5
	v_cvt_u32_f32_e32 v183, v183
	v_fma_f32 v133, v9, v171, v133
	v_add_f32_e32 v182, 1.0, v182
	v_rcp_f32_e32 v182, v182
	v_min_u32_sdwa v183, v183, s50 dst_sel:BYTE_3 dst_unused:UNUSED_PAD src0_sel:DWORD src1_sel:DWORD
	v_fma_f32 v182, v182, s82, 0.5
	v_cvt_u32_f32_e32 v182, v182
	v_exp_f32_e32 v132, v132
	v_exp_f32_e32 v133, v133
	v_rcp_f32_e32 v140, v140
	v_min_u32_sdwa v182, v182, s50 dst_sel:WORD_1 dst_unused:UNUSED_PAD src0_sel:DWORD src1_sel:DWORD
	v_add_f32_e32 v132, 1.0, v132
	v_or3_b32 v182, v144, v182, v183
	v_fma_f32 v144, v16, v170, v128
	v_fma_f32 v183, v17, v170, v129
	v_fma_f32 v128, v0, v171, v128
	v_fma_f32 v129, v1, v171, v129
	v_exp_f32_e32 v144, v144
	v_exp_f32_e32 v183, v183
	v_exp_f32_e32 v128, v128
	v_exp_f32_e32 v129, v129
	v_add_f32_e32 v144, 1.0, v144
	v_add_f32_e32 v183, 1.0, v183
	v_add_f32_e32 v133, 1.0, v133
	v_add_f32_e32 v128, 1.0, v128
	v_add_f32_e32 v129, 1.0, v129
	v_rcp_f32_e32 v144, v144
	v_rcp_f32_e32 v183, v183
	v_rcp_f32_e32 v141, v141
	v_rcp_f32_e32 v136, v136
	v_rcp_f32_e32 v137, v137
	v_rcp_f32_e32 v132, v132
	v_rcp_f32_e32 v133, v133
	v_rcp_f32_e32 v128, v128
	v_rcp_f32_e32 v129, v129
	v_fma_f32 v144, v144, s82, 0.5
	v_fma_f32 v183, v183, s82, 0.5
	v_fma_f32 v140, v140, s82, 0.5
	v_fma_f32 v141, v141, s82, 0.5
	v_fma_f32 v136, v136, s82, 0.5
	v_fma_f32 v137, v137, s82, 0.5
	v_fma_f32 v132, v132, s82, 0.5
	v_fma_f32 v133, v133, s82, 0.5
	v_fma_f32 v128, v128, s82, 0.5
	v_fma_f32 v129, v129, s82, 0.5
	v_cvt_u32_f32_e32 v144, v144
; __device__ __forceinline__ float sigm(float x) { return __builtin_amdgcn_rcpf(1.f + __expf(-x)); }
;     __device__ __forceinline__ void operator()(const f32x4 (&acc)[2][2][4][2], const Unit& u, int wr, int wc, int fr, int fq) const {
;     ...
;             for (int ai = 0; ai < 2; ++ai)
; #pragma unroll
;                 for (int m = 0; m < 4; ++m) { unsigned char* rp = S + ((size_t)(((g >> 2) * (MT / 256) + u.pm) * 8 + (g & 3) * 2) * 256 + ai * HALF + wr * 64 + m * 16 + fr) * 128 + wc * 32 + 8 * fq;
; #pragma unroll
;                     for (int bj = 0; bj < 2; ++bj) { u32x2 w;
; #pragma unroll
;                         for (int n = 0; n < 2; ++n) { const f32x4 v = acc[ai][bj][m][n] * rs[ai][m] + bv[bj][n]; unsigned q = 0;
; #pragma unroll
;                             for (int j = 0; j < 4; ++j) { const unsigned b = (unsigned)(sigm(v[j]) * 255.f + 0.5f); q |= (b > 255u ? 255u : b) << (8 * j); }
;                             if (n == 0) w.x = q; else w.y = q; }
;                         *(u32x2*)(rp + (size_t)bj * 32768) = w; } }
	v_cvt_u32_f32_e32 v183, v183
	v_cvt_u32_f32_e32 v140, v140
	v_cvt_u32_f32_e32 v141, v141
	v_cvt_u32_f32_e32 v136, v136
	v_cvt_u32_f32_e32 v137, v137
	v_cvt_u32_f32_e32 v132, v132
	v_cvt_u32_f32_e32 v133, v133
	v_cvt_u32_f32_e32 v128, v128
	v_cvt_u32_f32_e32 v129, v129
	v_lshl_or_b32 v144, v183, 8, v144
	v_fma_f32 v183, v18, v170, v130
	v_fma_f32 v184, v19, v170, v131
	v_lshl_or_b32 v140, v141, 8, v140
	v_fma_f32 v141, v14, v171, v142
	v_fmac_f32_e32 v143, v15, v171
	v_lshl_or_b32 v136, v137, 8, v136
	v_fma_f32 v137, v6, v171, v138
	v_fmac_f32_e32 v139, v7, v171
	v_lshl_or_b32 v132, v133, 8, v132
	v_fma_f32 v133, v10, v171, v134
	v_fmac_f32_e32 v135, v11, v171
	v_lshl_or_b32 v128, v129, 8, v128
	v_fma_f32 v129, v2, v171, v130
	v_fmac_f32_e32 v131, v3, v171
	v_mov_b32_e32 v142, v143
	v_mov_b32_e32 v138, v139
	v_mov_b32_e32 v134, v135
	v_mov_b32_e32 v130, v131
	v_exp_f32_e32 v183, v183
	v_exp_f32_e32 v184, v184
	v_exp_f32_e32 v141, v141
	v_exp_f32_e32 v142, v142
	v_exp_f32_e32 v137, v137
	v_exp_f32_e32 v138, v138
	v_exp_f32_e32 v133, v133
	v_exp_f32_e32 v134, v134
	v_exp_f32_e32 v129, v129
	v_exp_f32_e32 v130, v130
	v_add_f32_e32 v183, 1.0, v183
	v_add_f32_e32 v184, 1.0, v184
	v_add_f32_e32 v141, 1.0, v141
	v_add_f32_e32 v142, 1.0, v142
	v_add_f32_e32 v137, 1.0, v137
	v_add_f32_e32 v138, 1.0, v138
	v_add_f32_e32 v133, 1.0, v133
	v_add_f32_e32 v134, 1.0, v134
	v_add_f32_e32 v129, 1.0, v129
	v_add_f32_e32 v130, 1.0, v130
	v_rcp_f32_e32 v183, v183
	v_rcp_f32_e32 v184, v184
	v_rcp_f32_e32 v141, v141
	v_rcp_f32_e32 v142, v142
	v_rcp_f32_e32 v137, v137
	v_rcp_f32_e32 v138, v138
	v_rcp_f32_e32 v133, v133
	v_rcp_f32_e32 v134, v134
	v_rcp_f32_e32 v129, v129
	v_rcp_f32_e32 v130, v130
	v_fma_f32 v183, v183, s82, 0.5
	v_fma_f32 v184, v184, s82, 0.5
	v_fma_f32 v141, v141, s82, 0.5
	v_fma_f32 v142, v142, s82, 0.5
	v_fma_f32 v137, v137, s82, 0.5
	v_fma_f32 v138, v138, s82, 0.5
	v_fma_f32 v133, v133, s82, 0.5
	v_fma_f32 v134, v134, s82, 0.5
	v_fma_f32 v129, v129, s82, 0.5
	v_fma_f32 v130, v130, s82, 0.5
	v_cvt_u32_f32_e32 v183, v183
	v_cvt_u32_f32_e32 v184, v184
	v_cvt_u32_f32_e32 v141, v141
	v_cvt_u32_f32_e32 v142, v142
	v_cvt_u32_f32_e32 v137, v137
	v_cvt_u32_f32_e32 v138, v138
	v_cvt_u32_f32_e32 v133, v133
	v_cvt_u32_f32_e32 v134, v134
	v_cvt_u32_f32_e32 v129, v129
	v_cvt_u32_f32_e32 v130, v130
	v_min_u32_sdwa v183, v183, s50 dst_sel:WORD_1 dst_unused:UNUSED_PAD src0_sel:DWORD src1_sel:DWORD
	v_min_u32_sdwa v184, v184, s50 dst_sel:BYTE_3 dst_unused:UNUSED_PAD src0_sel:DWORD src1_sel:DWORD
	v_min_u32_sdwa v141, v141, s50 dst_sel:WORD_1 dst_unused:UNUSED_PAD src0_sel:DWORD src1_sel:DWORD
	v_min_u32_sdwa v142, v142, s50 dst_sel:BYTE_3 dst_unused:UNUSED_PAD src0_sel:DWORD src1_sel:DWORD
	v_min_u32_sdwa v137, v137, s50 dst_sel:WORD_1 dst_unused:UNUSED_PAD src0_sel:DWORD src1_sel:DWORD
	v_min_u32_sdwa v138, v138, s50 dst_sel:BYTE_3 dst_unused:UNUSED_PAD src0_sel:DWORD src1_sel:DWORD
	v_min_u32_sdwa v133, v133, s50 dst_sel:WORD_1 dst_unused:UNUSED_PAD src0_sel:DWORD src1_sel:DWORD
	v_min_u32_sdwa v134, v134, s50 dst_sel:BYTE_3 dst_unused:UNUSED_PAD src0_sel:DWORD src1_sel:DWORD
	v_min_u32_sdwa v129, v129, s50 dst_sel:WORD_1 dst_unused:UNUSED_PAD src0_sel:DWORD src1_sel:DWORD
	v_min_u32_sdwa v130, v130, s50 dst_sel:BYTE_3 dst_unused:UNUSED_PAD src0_sel:DWORD src1_sel:DWORD
	v_or3_b32 v183, v144, v183, v184
	v_or3_b32 v140, v140, v141, v142
	v_or3_b32 v141, v136, v137, v138
	v_or3_b32 v132, v132, v133, v134
	v_or3_b32 v133, v128, v129, v130
	global_store_dwordx2 v[178:179], v[182:183], off
	global_store_dwordx2 v[180:181], v[140:141], off offset:2048
	global_store_dwordx2 v[178:179], v[132:133], off offset:2048
